# m1b: M1 part B K/V tile loads (4 per item) hoisted above gate stage into fresh regs
# baseline (speedup 1.0000x reference)
;   __host__ __device__ __forceinline__ float* G() const { return (float*)(wsl() + OFF_G); }
;   __host__ __device__ __forceinline__ float* mloc() const { return (float*)(wsl() + OFF_MLOC); }
;   __host__ __device__ __forceinline__ float* bend() const { return (float*)(wsl() + OFF_BEND); }
;   __host__ __device__ __forceinline__ bf16_t* ACT() const { return (bf16_t*)(wsl() + OFF_ACT); }
; __device__ __forceinline__ float logsigmoidf_(float x) { return fminf(x, 0.0f) - log1pf(__expf(-fabsf(x))); }
; __device__ __forceinline__ int obid() { int t = blockIdx.x; asm volatile("" : "+s"(t)); return t; }
; __device__ __forceinline__ void m1_phase(const Params& p, char* smem) {
;     ...
;   for (int it = obid(); it < NCHAIN * NCHUNK; it += gridDim.x) {
;     int ci = it / NCHUNK, j = it - ci * NCHUNK;
;     int dir = ci & 1, h = (ci >> 1) & 3, b = ci >> 3;
;     int rowbase = b * TPB;
;     if (w == 0) {
;       int row = rowbase + mchunk_tok(dir, j, lane);
;       float gi = p.G()[(size_t)row * 16 + (2 * dir) * 4 + h] + p.mlstm_gate_b[(2 * dir) * 4 + h];
;       float gf = p.G()[(size_t)row * 16 + (2 * dir + 1) * 4 + h] + p.mlstm_gate_b[(2 * dir + 1) * 4 + h];
;       float bsum = logsigmoidf_(gf);
; #pragma unroll
;       for (int o = 1; o < 64; o <<= 1) { float t = __shfl_up(bsum, o); if (lane >= o) bsum += t; }
;       float be = __shfl(bsum, 63);
;       float gg = be - bsum + gi;
;       float ml = wave_max(gg);
;       wv[lane] = __expf(gg - ml);
;       if (lane == 0) { p.mloc()[it] = ml; p.bend()[it] = be; }
;     }
;     __syncthreads();
; #pragma unroll
;     for (int i = 0; i < 2; ++i) {
;       int idx = tid + i * NTHR;
;       int r = idx & 63, fc = (idx >> 6) * 8;
;       int row = rowbase + mchunk_tok(dir, j, r);
;       const bf16_t* src = p.ACT() + (size_t)row * PW;
;       uint4 kv = *(const uint4*)(src + 1184 + h * 128 + fc);
;       uint4 vv = *(const uint4*)(src + 1696 + h * 128 + fc);
.LBB0_768:
	s_mul_hi_i32 s2, s56, 0x3e0f83e1
	s_lshr_b32 s3, s2, 31
	s_ashr_i32 s2, s2, 5
	s_add_i32 s2, s2, s3
	s_mul_i32 s12, s2, 0xffffff7c
	s_lshr_b32 s11, s2, 3
	s_add_i32 s12, s12, s56
	s_and_b32 s13, s2, 1
	s_bfe_u32 s10, s2, 0x20001
	s_mulk_i32 s11, 0x2100
	s_cmp_eq_u32 s13, 0
	s_cselect_b64 vcc, -1, 0
	s_cmp_gt_i32 s12, 3
	s_cselect_b32 s60, 0x87, 3
	s_sub_i32 s60, s60, s12
	s_lshl_b32 s60, s60, 6
	v_bitop3_b32 v136, s60, 63, v10 bitop3:0x36
	v_lshl_or_b32 v137, s12, 6, v10
	v_cndmask_b32_e32 v136, v136, v137, vcc
	v_add_u32_e32 v138, s11, v136
	v_mov_b64_e32 v[136:137], s[58:59]
	v_mad_i64_i32 v[136:137], s[60:61], v138, s84, v[136:137]
	s_lshl_b32 s30, s10, 8
	v_lshl_add_u64 v[140:141], v[136:137], 0, s[30:31]
	v_lshl_add_u64 v[142:143], v[14:15], 1, v[140:141]
	v_lshl_add_u64 v[144:145], v[16:17], 1, v[140:141]
	global_load_dwordx4 v[120:123], v[142:143], off offset:2368
	global_load_dwordx4 v[124:127], v[142:143], off offset:3392
	global_load_dwordx4 v[128:131], v[144:145], off offset:2368
	global_load_dwordx4 v[132:135], v[144:145], off offset:3392
	s_and_saveexec_b64 s[4:5], s[40:41]
	s_cbranch_execz .LBB0_775
	s_cmp_lg_u32 s13, 0
	s_mov_b64 s[2:3], -1
	s_cbranch_scc0 .LBB0_771
	s_cmp_gt_i32 s12, 3
	s_cselect_b32 s2, 0x87, 3
	s_sub_i32 s2, s2, s12
	s_lshl_b32 s2, s2, 6
	v_bitop3_b32 v0, s2, 63, v8 bitop3:0x36
	s_mov_b64 s[2:3], 0

;   __host__ __device__ __forceinline__ bf16_t* ACT() const { return (bf16_t*)(wsl() + OFF_ACT); }
; __device__ __forceinline__ float bf2f(bf16_t h) { return __uint_as_float(((uint32_t)h) << 16); }
; __device__ __forceinline__ void m1_phase(const Params& p, char* smem) {
;     ...
;     __syncthreads();
; #pragma unroll
;     for (int i = 0; i < 2; ++i) {
;       int idx = tid + i * NTHR;
;       int r = idx & 63, fc = (idx >> 6) * 8;
;       int row = rowbase + mchunk_tok(dir, j, r);
;       const bf16_t* src = p.ACT() + (size_t)row * PW;
;       uint4 kv = *(const uint4*)(src + 1184 + h * 128 + fc);
;       uint4 vv = *(const uint4*)(src + 1696 + h * 128 + fc);
;       float wr = wv[r];
;       const bf16_t* ke = (const bf16_t*)&kv; const bf16_t* ve = (const bf16_t*)&vv;
; #pragma unroll
;       for (int e = 0; e < 8; ++e) {
;         Kt[(fc + e) * 72 + r] = ke[e];
;         Vt[(fc + e) * 72 + r] = f2bf(bf2f(ve[e]) * wr);
;       }
;     }
;     __syncthreads();
.LBB0_775:
	s_or_b64 exec, exec, s[4:5]
	s_cmp_eq_u32 s13, 0
	s_cselect_b64 vcc, -1, 0
	s_cmp_gt_i32 s12, 3
	s_cselect_b32 s2, 0x87, 3
	s_sub_i32 s2, s2, s12
	s_lshl_b32 s2, s2, 6
	v_bitop3_b32 v0, s2, 63, v10 bitop3:0x36
	v_lshl_or_b32 v1, s12, 6, v10
	v_cndmask_b32_e32 v0, v0, v1, vcc
	v_add_u32_e32 v2, s11, v0
	v_mov_b64_e32 v[0:1], s[58:59]
	v_mad_i64_i32 v[0:1], s[2:3], v2, s84, v[0:1]
	s_lshl_b32 s30, s10, 8
	v_lshl_add_u64 v[44:45], v[0:1], 0, s[30:31]
	v_lshl_add_u64 v[4:5], v[14:15], 1, v[44:45]
	s_waitcnt vmcnt(0) lgkmcnt(0)
	s_barrier
	ds_read_b32 v42, v11 offset:36864
	s_ashr_i32 s57, s56, 31
	s_lshl_b64 s[2:3], s[56:57], 15
	s_add_u32 s4, s8, s2
	s_addc_u32 s5, s9, s3
	s_waitcnt vmcnt(1)
	ds_write_b16 v38, v120
	s_waitcnt vmcnt(0)
	v_lshlrev_b32_e32 v43, 16, v124
	s_waitcnt lgkmcnt(1)
	v_mul_f32_e32 v43, v42, v43
	v_bfe_u32 v46, v43, 16, 1
	v_add3_u32 v43, v43, v46, s28
	ds_write_b16_d16_hi v38, v43 offset:18432
	ds_write_b16_d16_hi v38, v120 offset:144
	v_and_b32_e32 v0, 0xffff0000, v124
	v_mul_f32_e32 v0, v42, v0
	v_bfe_u32 v4, v0, 16, 1
	v_add3_u32 v0, v0, v4, s28
	ds_write_b16_d16_hi v38, v0 offset:18576
	ds_write_b16 v38, v121 offset:288
	v_lshlrev_b32_e32 v0, 16, v125
	v_mul_f32_e32 v0, v42, v0
	v_bfe_u32 v4, v0, 16, 1
	v_add3_u32 v0, v0, v4, s28
	ds_write_b16_d16_hi v38, v0 offset:18720
	ds_write_b16_d16_hi v38, v121 offset:432
	v_and_b32_e32 v0, 0xffff0000, v125
	v_mul_f32_e32 v0, v42, v0
	v_bfe_u32 v1, v0, 16, 1
	v_add3_u32 v0, v0, v1, s28
	ds_write_b16_d16_hi v38, v0 offset:18864
	ds_write_b16 v38, v122 offset:576
	v_lshlrev_b32_e32 v0, 16, v126
	v_mul_f32_e32 v0, v42, v0
	v_bfe_u32 v1, v0, 16, 1
	v_add3_u32 v0, v0, v1, s28
	ds_write_b16_d16_hi v38, v0 offset:19008
	ds_write_b16_d16_hi v38, v122 offset:720
	v_and_b32_e32 v0, 0xffff0000, v126
	v_mul_f32_e32 v0, v42, v0
	v_bfe_u32 v1, v0, 16, 1
	v_add3_u32 v0, v0, v1, s28
	ds_write_b16_d16_hi v38, v0 offset:19152
	ds_write_b16 v38, v123 offset:864
	v_lshlrev_b32_e32 v0, 16, v127
	v_mul_f32_e32 v0, v42, v0
	v_bfe_u32 v1, v0, 16, 1
	v_add3_u32 v0, v0, v1, s28
	ds_write_b16_d16_hi v38, v0 offset:19296
	ds_write_b16_d16_hi v39, v123
	v_and_b32_e32 v0, 0xffff0000, v127
	v_mul_f32_e32 v0, v42, v0
	v_bfe_u32 v1, v0, 16, 1
	v_add3_u32 v0, v0, v1, s28
	ds_write_b16_d16_hi v39, v0 offset:18432
	v_lshl_add_u64 v[4:5], v[16:17], 1, v[44:45]
	s_waitcnt vmcnt(1)
	ds_write_b16 v40, v128
	s_waitcnt vmcnt(0)
	v_lshlrev_b32_e32 v43, 16, v132
	v_mul_f32_e32 v43, v42, v43
	v_bfe_u32 v44, v43, 16, 1
	v_add3_u32 v43, v43, v44, s28
	ds_write_b16_d16_hi v40, v43 offset:18432
	ds_write_b16_d16_hi v40, v128 offset:144
	v_and_b32_e32 v0, 0xffff0000, v132
	v_mul_f32_e32 v0, v42, v0
	v_bfe_u32 v4, v0, 16, 1
	v_add3_u32 v0, v0, v4, s28
	ds_write_b16_d16_hi v40, v0 offset:18576
	ds_write_b16 v40, v129 offset:288
	v_lshlrev_b32_e32 v0, 16, v133
	v_mul_f32_e32 v0, v42, v0
	v_bfe_u32 v4, v0, 16, 1
	v_add3_u32 v0, v0, v4, s28
	ds_write_b16_d16_hi v40, v0 offset:18720
	ds_write_b16_d16_hi v40, v129 offset:432
	v_and_b32_e32 v0, 0xffff0000, v133
	v_mul_f32_e32 v0, v42, v0
	v_bfe_u32 v1, v0, 16, 1
	v_add3_u32 v0, v0, v1, s28
	ds_write_b16_d16_hi v40, v0 offset:18864
	ds_write_b16 v40, v130 offset:576
	v_lshlrev_b32_e32 v0, 16, v134
	v_mul_f32_e32 v0, v42, v0
	v_bfe_u32 v1, v0, 16, 1
	v_add3_u32 v0, v0, v1, s28
	ds_write_b16_d16_hi v40, v0 offset:19008
	ds_write_b16_d16_hi v40, v130 offset:720
	v_and_b32_e32 v0, 0xffff0000, v134
	v_mul_f32_e32 v0, v42, v0
	v_bfe_u32 v1, v0, 16, 1
	v_add3_u32 v0, v0, v1, s28
	ds_write_b16_d16_hi v40, v0 offset:19152
	ds_write_b16 v40, v131 offset:864
	v_lshlrev_b32_e32 v0, 16, v135
	v_mul_f32_e32 v0, v42, v0
	v_bfe_u32 v1, v0, 16, 1
	v_add3_u32 v0, v0, v1, s28
	ds_write_b16_d16_hi v40, v0 offset:19296
	ds_write_b16_d16_hi v41, v131
	v_and_b32_e32 v0, 0xffff0000, v135
	v_mul_f32_e32 v0, v42, v0
	v_bfe_u32 v1, v0, 16, 1
	v_add3_u32 v0, v0, v1, s28
	ds_write_b16_d16_hi v41, v0 offset:18432
	s_waitcnt lgkmcnt(0)
	s_barrier
;   __host__ __device__ __forceinline__ float* dn() const { return (float*)(wsl() + OFF_DN); }
;   __host__ __device__ __forceinline__ bf16_t* R() const { return (bf16_t*)(wsl() + OFF_R); }
; __device__ __forceinline__ float bf2f(bf16_t h) { return __uint_as_float(((uint32_t)h) << 16); }
; #define MFMA16(a, b, c) __builtin_amdgcn_mfma_f32_16x16x32_bf16(a, b, c, 0, 0, 0)
; __device__ __forceinline__ void m1_phase(const Params& p, char* smem) {
;     ...
;     f32x4 acc[8];
; #pragma unroll
;     for (int ni = 0; ni < 8; ++ni) acc[ni] = (f32x4){0.f, 0.f, 0.f, 0.f};
; #pragma unroll
;     for (int ks = 0; ks < 2; ++ks) {
;       bf16x8 a = *(const bf16x8*)(Vt + (w * 16 + fr) * 72 + ks * 32 + fq * 8);
; #pragma unroll
;       for (int ni = 0; ni < 8; ++ni) {
;         bf16x8 bb = *(const bf16x8*)(Kt + (ni * 16 + fr) * 72 + ks * 32 + fq * 8);
;         acc[ni] = MFMA16(a, bb, acc[ni]);
;       }
;     }
;     bf16_t* dC = p.R() + (size_t)it * 16384;
; #pragma unroll
;     for (int ni = 0; ni < 8; ++ni)
; #pragma unroll
;       for (int jj = 0; jj < 4; ++jj) dC[(w * 16 + fq * 4 + jj) * 128 + ni * 16 + fr] = f2bf(acc[ni][jj]);
;     if (tid < 128) {
;       float s = 0;
; #pragma unroll 8
;       for (int r = 0; r < 64; ++r) s += wv[r] * bf2f(Kt[tid * 72 + r]);
;       p.dn()[(size_t)it * 128 + tid] = s;
	ds_read_b128 v[0:3], v12 offset:18432
	ds_read_b128 v[4:7], v9
	ds_read_b128 v[42:45], v9 offset:2304
	ds_read_b128 v[46:49], v9 offset:4608
	ds_read_b128 v[50:53], v9 offset:6912
	ds_read_b128 v[54:57], v9 offset:9216
	ds_read_b128 v[58:61], v9 offset:11520
	ds_read_b128 v[62:65], v9 offset:13824
	ds_read_b128 v[66:69], v9 offset:16128
	s_waitcnt lgkmcnt(7)
	v_mfma_f32_16x16x32_bf16 v[4:7], v[0:3], v[4:7], 0
	s_waitcnt lgkmcnt(6)
	v_mfma_f32_16x16x32_bf16 v[42:45], v[0:3], v[42:45], 0
	s_waitcnt lgkmcnt(5)
	v_mfma_f32_16x16x32_bf16 v[46:49], v[0:3], v[46:49], 0
	s_waitcnt lgkmcnt(4)
	v_mfma_f32_16x16x32_bf16 v[50:53], v[0:3], v[50:53], 0
	s_waitcnt lgkmcnt(3)
	v_mfma_f32_16x16x32_bf16 v[54:57], v[0:3], v[54:57], 0
	s_waitcnt lgkmcnt(2)
	v_mfma_f32_16x16x32_bf16 v[58:61], v[0:3], v[58:61], 0
	s_waitcnt lgkmcnt(1)
	v_mfma_f32_16x16x32_bf16 v[62:65], v[0:3], v[62:65], 0
	s_waitcnt lgkmcnt(0)
	v_mfma_f32_16x16x32_bf16 v[0:3], v[0:3], v[66:69], 0
	ds_read_b128 v[66:69], v12 offset:18496
	ds_read_b128 v[70:73], v9 offset:64
	s_waitcnt lgkmcnt(0)
	v_mfma_f32_16x16x32_bf16 v[4:7], v[66:69], v[70:73], v[4:7]
	ds_read_b128 v[70:73], v9 offset:2368
	s_waitcnt lgkmcnt(0)
	v_mfma_f32_16x16x32_bf16 v[42:45], v[66:69], v[70:73], v[42:45]
	ds_read_b128 v[70:73], v9 offset:4672
	s_waitcnt lgkmcnt(0)
	v_mfma_f32_16x16x32_bf16 v[46:49], v[66:69], v[70:73], v[46:49]
	ds_read_b128 v[70:73], v9 offset:6976
	s_waitcnt lgkmcnt(0)
	v_mfma_f32_16x16x32_bf16 v[50:53], v[66:69], v[70:73], v[50:53]
	ds_read_b128 v[70:73], v9 offset:9280
	s_waitcnt lgkmcnt(0)
	v_mfma_f32_16x16x32_bf16 v[54:57], v[66:69], v[70:73], v[54:57]
	ds_read_b128 v[70:73], v9 offset:11584
	s_waitcnt lgkmcnt(0)
	v_mfma_f32_16x16x32_bf16 v[58:61], v[66:69], v[70:73], v[58:61]
	ds_read_b128 v[70:73], v9 offset:13888
	s_waitcnt lgkmcnt(0)
	v_mfma_f32_16x16x32_bf16 v[62:65], v[66:69], v[70:73], v[62:65]
	ds_read_b128 v[70:73], v9 offset:16192
	s_waitcnt lgkmcnt(0)
	v_mfma_f32_16x16x32_bf16 v[0:3], v[66:69], v[70:73], v[0:3]
	v_bfe_u32 v66, v4, 16, 1
	v_add3_u32 v4, v4, v66, s28
	v_lshl_add_u64 v[66:67], v[20:21], 1, s[4:5]
	global_store_short_d16_hi v[66:67], v4, off
	v_bfe_u32 v4, v5, 16, 1
	v_add3_u32 v66, v5, v4, s28
	v_lshl_add_u64 v[4:5], v[18:19], 1, s[4:5]
	global_store_short_d16_hi v[4:5], v66, off offset:256
	v_bfe_u32 v66, v6, 16, 1
	v_add3_u32 v6, v6, v66, s28
	global_store_short_d16_hi v[4:5], v6, off offset:512
	v_bfe_u32 v6, v7, 16, 1
	v_add3_u32 v6, v7, v6, s28
	global_store_short_d16_hi v[4:5], v6, off offset:768
	v_bfe_u32 v6, v42, 16, 1
	v_add3_u32 v6, v42, v6, s28
	global_store_short_d16_hi v[4:5], v6, off offset:32
	v_bfe_u32 v6, v43, 16, 1
	v_add3_u32 v42, v43, v6, s28
	v_lshl_add_u64 v[6:7], v[24:25], 1, s[4:5]
	global_store_short_d16_hi v[6:7], v42, off offset:256
	v_bfe_u32 v42, v44, 16, 1
	v_add3_u32 v42, v44, v42, s28
	global_store_short_d16_hi v[6:7], v42, off offset:512
	v_bfe_u32 v42, v45, 16, 1
	v_add3_u32 v42, v45, v42, s28
	global_store_short_d16_hi v[6:7], v42, off offset:768
	v_bfe_u32 v6, v46, 16, 1
	v_add3_u32 v6, v46, v6, s28
	global_store_short_d16_hi v[4:5], v6, off offset:64
	v_bfe_u32 v6, v47, 16, 1
	v_add3_u32 v42, v47, v6, s28
	v_lshl_add_u64 v[6:7], v[26:27], 1, s[4:5]
	global_store_short_d16_hi v[6:7], v42, off offset:256
	v_bfe_u32 v42, v48, 16, 1
	v_add3_u32 v42, v48, v42, s28
	global_store_short_d16_hi v[6:7], v42, off offset:512
	v_bfe_u32 v42, v49, 16, 1
	v_add3_u32 v42, v49, v42, s28
	global_store_short_d16_hi v[6:7], v42, off offset:768
	v_bfe_u32 v6, v50, 16, 1
	v_add3_u32 v6, v50, v6, s28
	global_store_short_d16_hi v[4:5], v6, off offset:96
	v_bfe_u32 v6, v51, 16, 1
	v_add3_u32 v42, v51, v6, s28
	v_lshl_add_u64 v[6:7], v[28:29], 1, s[4:5]
	global_store_short_d16_hi v[6:7], v42, off offset:256
	v_bfe_u32 v42, v52, 16, 1
	v_add3_u32 v42, v52, v42, s28
	global_store_short_d16_hi v[6:7], v42, off offset:512
	v_bfe_u32 v42, v53, 16, 1
	v_add3_u32 v42, v53, v42, s28
	global_store_short_d16_hi v[6:7], v42, off offset:768
	v_bfe_u32 v6, v54, 16, 1
	v_add3_u32 v6, v54, v6, s28
	global_store_short_d16_hi v[4:5], v6, off offset:128
	v_bfe_u32 v6, v55, 16, 1
	v_add3_u32 v42, v55, v6, s28
	v_lshl_add_u64 v[6:7], v[30:31], 1, s[4:5]
	global_store_short_d16_hi v[6:7], v42, off offset:256
	v_bfe_u32 v42, v56, 16, 1
	v_add3_u32 v42, v56, v42, s28
	global_store_short_d16_hi v[6:7], v42, off offset:512
	v_bfe_u32 v42, v57, 16, 1
	v_add3_u32 v42, v57, v42, s28
	global_store_short_d16_hi v[6:7], v42, off offset:768
	v_bfe_u32 v6, v58, 16, 1
	v_add3_u32 v6, v58, v6, s28
	global_store_short_d16_hi v[4:5], v6, off offset:160
	v_bfe_u32 v6, v59, 16, 1
	v_add3_u32 v42, v59, v6, s28
	v_lshl_add_u64 v[6:7], v[32:33], 1, s[4:5]
	global_store_short_d16_hi v[6:7], v42, off offset:256
	v_bfe_u32 v42, v60, 16, 1
	v_add3_u32 v42, v60, v42, s28
	global_store_short_d16_hi v[6:7], v42, off offset:512
	v_bfe_u32 v42, v61, 16, 1
	v_add3_u32 v42, v61, v42, s28
	global_store_short_d16_hi v[6:7], v42, off offset:768
	v_bfe_u32 v6, v62, 16, 1
	v_add3_u32 v6, v62, v6, s28
	global_store_short_d16_hi v[4:5], v6, off offset:192
	v_bfe_u32 v6, v63, 16, 1
	v_add3_u32 v42, v63, v6, s28
	v_lshl_add_u64 v[6:7], v[34:35], 1, s[4:5]
	global_store_short_d16_hi v[6:7], v42, off offset:256
	v_bfe_u32 v42, v64, 16, 1
	v_add3_u32 v42, v64, v42, s28
	global_store_short_d16_hi v[6:7], v42, off offset:512
	v_bfe_u32 v42, v65, 16, 1
	v_add3_u32 v42, v65, v42, s28
	global_store_short_d16_hi v[6:7], v42, off offset:768
	v_bfe_u32 v6, v0, 16, 1
	v_add3_u32 v0, v0, v6, s28
	global_store_short_d16_hi v[4:5], v0, off offset:224
	v_bfe_u32 v0, v1, 16, 1
	v_add3_u32 v4, v1, v0, s28
	v_lshl_add_u64 v[0:1], v[36:37], 1, s[4:5]
	global_store_short_d16_hi v[0:1], v4, off offset:256
	v_bfe_u32 v4, v2, 16, 1
	v_add3_u32 v2, v2, v4, s28
	global_store_short_d16_hi v[0:1], v2, off offset:512
	v_bfe_u32 v2, v3, 16, 1
	v_add3_u32 v2, v3, v2, s28
	global_store_short_d16_hi v[0:1], v2, off offset:768
	s_and_saveexec_b64 s[4:5], s[44:45]
	s_cbranch_execz .LBB0_767
	s_add_i32 s2, 0, 0x9000
	v_mov_b32_e32 v0, 0
	s_mov_b32 s3, 0
